# v36 + attention QK^T: K fragments preloaded into 11 free VGPR quads, chained MFMAs with counted lgkmcnt (was one LDS round trip per MFMA)
# speedup vs baseline: 1.0214x; 1.0214x over previous
.LBB0_373:
	s_add_i32 s23, s11, 0xffffff80
	s_add_i32 s22, s54, s11
	s_add_u32 s0, s52, s44
	s_addc_u32 s1, s53, s43
	s_lshl_b32 s38, s10, 7
	s_ashr_i32 s39, s38, 31
	s_lshl_b64 s[38:39], s[38:39], 1
	s_add_u32 s79, s0, s38
	s_addc_u32 s80, s1, s39
	s_add_u32 s67, s79, 0x1800
	s_addc_u32 s68, s80, 0
	s_max_i32 s0, s11, 64
	s_sub_i32 s0, s0, 64
	s_mul_hi_u32 s45, s0, s40
	s_mul_i32 s44, s0, s40
	s_lshl_b64 s[44:45], s[44:45], 1
	s_add_u32 s44, s67, s44
	s_addc_u32 s45, s68, s45
	s_add_i32 s63, s41, 0
	s_add_i32 s71, s63, 0x4000
	v_or_b32_e32 v194, v3, v146
	s_add_i32 s70, s63, 0x4400
	s_lshl_b64 s[6:7], s[6:7], 1
	v_ashrrev_i32_e32 v173, 8, v1
	v_lshl_add_u64 v[4:5], v[194:195], 1, s[44:45]
	s_mov_b32 m0, s71
	s_add_u32 s44, s79, s6
	v_mul_lo_u32 v1, v173, s40
	global_load_lds_dwordx4 v[4:5], off
	v_lshl_add_u64 v[4:5], v[4:5], 0, s[82:83]
	s_mov_b32 m0, s70
	s_addc_u32 s45, s80, s7
	v_or_b32_e32 v134, v1, v145
	v_mov_b32_e32 v135, v195
	global_load_lds_dwordx4 v[4:5], off
	v_lshl_add_u64 v[4:5], v[134:135], 1, s[44:45]
	v_or_b32_e32 v136, v162, v2
	v_mov_b32_e32 v137, v195
	s_add_i32 m0, s63, 0x10000
	v_lshl_add_u64 v[4:5], v[4:5], 0, s[86:87]
	v_lshl_add_u64 v[2:3], v[136:137], 1, s[44:45]
	global_load_lds_dwordx4 v[4:5], off
	v_lshl_add_u64 v[2:3], v[2:3], 0, s[86:87]
	s_add_i32 m0, s63, 0x10400
	s_cmp_eq_u32 s11, 0
	global_load_lds_dwordx4 v[2:3], off
	s_cselect_b64 s[44:45], -1, 0
	s_or_b32 s43, s22, 31
	s_cmp_gt_i32 s23, s43
	s_cselect_b64 s[48:49], -1, 0
	s_or_b64 s[44:45], s[44:45], s[48:49]
	s_sub_i32 s0, s22, 63
	s_cmp_lt_i32 s11, s0
	s_cselect_b64 s[48:49], -1, 0
	s_or_b64 s[44:45], s[44:45], s[48:49]
	v_add_u32_e32 v1, s22, v141
	s_and_b64 vcc, exec, s[44:45]
	s_cbranch_vccnz .LBB0_377
	s_cmp_gt_u32 s37, -3
	ds_read_b128 v[204:207], v163 offset:32768
	ds_read_b128 v[208:211], v164 offset:32768
	ds_read_b128 v[212:215], v165 offset:32768
	ds_read_b128 v[216:219], v166 offset:32768
	ds_read_b128 v[220:223], v163 offset:32896
	ds_read_b128 v[224:227], v164 offset:32896
	ds_read_b128 v[228:231], v165 offset:32896
	ds_read_b128 v[240:243], v166 offset:32896
	ds_read_b128 v[244:247], v163 offset:40960
	ds_read_b128 v[248:251], v164 offset:40960
	ds_read_b128 v[190:193], v165 offset:40960
	s_waitcnt lgkmcnt(10)
	v_mfma_f32_32x32x16_bf16 v[18:33], v[204:207], v[126:129], 0
	s_waitcnt lgkmcnt(9)
	v_mfma_f32_32x32x16_bf16 v[18:33], v[208:211], v[118:121], v[18:33]
	s_waitcnt lgkmcnt(8)
	v_mfma_f32_32x32x16_bf16 v[18:33], v[212:215], v[122:125], v[18:33]
	s_waitcnt lgkmcnt(7)
	v_mfma_f32_32x32x16_bf16 v[18:33], v[216:219], v[114:117], v[18:33]
	s_waitcnt lgkmcnt(6)
	v_mfma_f32_32x32x16_bf16 v[18:33], v[220:223], v[110:113], v[18:33]
	ds_read_b128 v[204:207], v166 offset:40960
	ds_read_b128 v[208:211], v163 offset:41088
	ds_read_b128 v[212:215], v164 offset:41088
	ds_read_b128 v[216:219], v165 offset:41088
	ds_read_b128 v[220:223], v166 offset:41088
	s_waitcnt lgkmcnt(10)
	v_mfma_f32_32x32x16_bf16 v[18:33], v[224:227], v[106:109], v[18:33]
	s_waitcnt lgkmcnt(9)
	v_mfma_f32_32x32x16_bf16 v[18:33], v[228:231], v[102:105], v[18:33]
	s_waitcnt lgkmcnt(8)
	v_mfma_f32_32x32x16_bf16 v[18:33], v[240:243], v[98:101], v[18:33]
	s_waitcnt lgkmcnt(7)
	v_mfma_f32_32x32x16_bf16 v[2:17], v[244:247], v[126:129], 0
	s_waitcnt lgkmcnt(6)
	v_mfma_f32_32x32x16_bf16 v[2:17], v[248:251], v[118:121], v[2:17]
	s_waitcnt lgkmcnt(5)
	v_mfma_f32_32x32x16_bf16 v[2:17], v[190:193], v[122:125], v[2:17]
	s_waitcnt lgkmcnt(4)
	v_mfma_f32_32x32x16_bf16 v[2:17], v[204:207], v[114:117], v[2:17]
	s_waitcnt lgkmcnt(3)
	v_mfma_f32_32x32x16_bf16 v[2:17], v[208:211], v[110:113], v[2:17]
	s_waitcnt lgkmcnt(2)
	v_mfma_f32_32x32x16_bf16 v[2:17], v[212:215], v[106:109], v[2:17]
	s_waitcnt lgkmcnt(1)
	v_mfma_f32_32x32x16_bf16 v[2:17], v[216:219], v[102:105], v[2:17]
	s_waitcnt lgkmcnt(0)
	v_mfma_f32_32x32x16_bf16 v[2:17], v[220:223], v[98:101], v[2:17]
	s_cbranch_scc1 .LBB0_376
	v_subrev_u32_e32 v34, s23, v1
	s_movk_i32 s0, 0x81
	v_cmp_gt_u32_e32 vcc, s0, v34
	v_add_u32_e32 v35, 0xffffff5f, v34
	s_nop 3
	v_cndmask_b32_e32 v18, v234, v18, vcc
	v_cmp_lt_u32_e32 vcc, s69, v35
	v_add_u32_e32 v35, 0xffffff7e, v34
	s_nop 0
	v_cndmask_b32_e32 v2, v234, v2, vcc
	v_cmp_lt_u32_e32 vcc, s69, v35
	v_add_u32_e32 v35, 0xffffff5e, v34
	s_nop 0
	v_cndmask_b32_e32 v19, v234, v19, vcc
	v_cmp_lt_u32_e32 vcc, s69, v35
	v_add_u32_e32 v35, 0xffffff7d, v34
	s_nop 0
	v_cndmask_b32_e32 v3, v234, v3, vcc
	v_cmp_lt_u32_e32 vcc, s69, v35
	v_add_u32_e32 v35, 0xffffff5d, v34
	s_nop 0
	v_cndmask_b32_e32 v20, v234, v20, vcc
	v_cmp_lt_u32_e32 vcc, s69, v35
	v_add_u32_e32 v35, 0xffffff7c, v34
	s_nop 0
	v_cndmask_b32_e32 v4, v234, v4, vcc
	v_cmp_lt_u32_e32 vcc, s69, v35
	v_add_u32_e32 v35, 0xffffff5c, v34
	s_nop 0
	v_cndmask_b32_e32 v21, v234, v21, vcc
	v_cmp_lt_u32_e32 vcc, s69, v35
	v_add_u32_e32 v35, 0xffffff77, v34
	s_nop 0
	v_cndmask_b32_e32 v5, v234, v5, vcc
	v_cmp_lt_u32_e32 vcc, s69, v35
	v_add_u32_e32 v35, 0xffffff57, v34
	s_nop 0
	v_cndmask_b32_e32 v22, v234, v22, vcc
	v_cmp_lt_u32_e32 vcc, s69, v35
	v_add_u32_e32 v35, 0xffffff76, v34
	s_nop 0
	v_cndmask_b32_e32 v6, v234, v6, vcc
	v_cmp_lt_u32_e32 vcc, s69, v35
	v_add_u32_e32 v35, 0xffffff56, v34
	s_nop 0
	v_cndmask_b32_e32 v23, v234, v23, vcc
	v_cmp_lt_u32_e32 vcc, s69, v35
	v_add_u32_e32 v35, 0xffffff75, v34
	s_nop 0
	v_cndmask_b32_e32 v7, v234, v7, vcc
	v_cmp_lt_u32_e32 vcc, s69, v35
	v_add_u32_e32 v35, 0xffffff55, v34
	s_nop 0
	v_cndmask_b32_e32 v24, v234, v24, vcc
	v_cmp_lt_u32_e32 vcc, s69, v35
	v_add_u32_e32 v35, 0xffffff74, v34
	s_nop 0
	v_cndmask_b32_e32 v8, v234, v8, vcc
	v_cmp_lt_u32_e32 vcc, s69, v35
	v_add_u32_e32 v35, 0xffffff54, v34
	s_nop 0
	v_cndmask_b32_e32 v25, v234, v25, vcc
	v_cmp_lt_u32_e32 vcc, s69, v35
	v_add_u32_e32 v35, 0xffffff6f, v34
	s_nop 0
	v_cndmask_b32_e32 v9, v234, v9, vcc
	v_cmp_lt_u32_e32 vcc, s69, v35
	v_add_u32_e32 v35, 0xffffff4f, v34
	s_nop 0
	v_cndmask_b32_e32 v26, v234, v26, vcc
	v_cmp_lt_u32_e32 vcc, s69, v35
	v_add_u32_e32 v35, 0xffffff6e, v34
	s_nop 0
	v_cndmask_b32_e32 v10, v234, v10, vcc
	v_cmp_lt_u32_e32 vcc, s69, v35
	v_add_u32_e32 v35, 0xffffff4e, v34
	s_nop 0
	v_cndmask_b32_e32 v27, v234, v27, vcc
	v_cmp_lt_u32_e32 vcc, s69, v35
	v_add_u32_e32 v35, 0xffffff6d, v34
	s_nop 0
	v_cndmask_b32_e32 v11, v234, v11, vcc
	v_cmp_lt_u32_e32 vcc, s69, v35
	v_add_u32_e32 v35, 0xffffff4d, v34
	s_nop 0
	v_cndmask_b32_e32 v28, v234, v28, vcc
	v_cmp_lt_u32_e32 vcc, s69, v35
	v_add_u32_e32 v35, 0xffffff6c, v34
	s_nop 0
	v_cndmask_b32_e32 v12, v234, v12, vcc
	v_cmp_lt_u32_e32 vcc, s69, v35
	v_add_u32_e32 v35, 0xffffff4c, v34
	s_nop 0
	v_cndmask_b32_e32 v29, v234, v29, vcc
	v_cmp_lt_u32_e32 vcc, s69, v35
	v_add_u32_e32 v35, 0xffffff67, v34
	s_nop 0
	v_cndmask_b32_e32 v13, v234, v13, vcc
	v_cmp_lt_u32_e32 vcc, s69, v35
	v_add_u32_e32 v35, 0xffffff47, v34
	s_nop 0
	v_cndmask_b32_e32 v30, v234, v30, vcc
	v_cmp_lt_u32_e32 vcc, s69, v35
	v_add_u32_e32 v35, 0xffffff66, v34
	s_nop 0
	v_cndmask_b32_e32 v14, v234, v14, vcc
	v_cmp_lt_u32_e32 vcc, s69, v35
	v_add_u32_e32 v35, 0xffffff46, v34
	s_nop 0
	v_cndmask_b32_e32 v31, v234, v31, vcc
	v_cmp_lt_u32_e32 vcc, s69, v35
	v_add_u32_e32 v35, 0xffffff65, v34
	s_nop 0
	v_cndmask_b32_e32 v15, v234, v15, vcc
	v_cmp_lt_u32_e32 vcc, s69, v35
	v_add_u32_e32 v35, 0xffffff45, v34
	s_nop 0
	v_cndmask_b32_e32 v32, v234, v32, vcc
	v_cmp_lt_u32_e32 vcc, s69, v35
	v_add_u32_e32 v35, 0xffffff64, v34
	v_add_u32_e32 v34, 0xffffff44, v34
	v_cndmask_b32_e32 v16, v234, v16, vcc
	v_cmp_lt_u32_e32 vcc, s69, v35
	s_nop 1
	v_cndmask_b32_e32 v33, v234, v33, vcc
	v_cmp_lt_u32_e32 vcc, s69, v34
	s_nop 1
	v_cndmask_b32_e32 v17, v234, v17, vcc

.LBB0_378:
	s_ashr_i32 s23, s51, 31
	s_add_i32 s41, s63, 0x8000
	s_add_u32 s6, s67, s6
	s_addc_u32 s7, s68, s7
	s_or_b32 s44, s11, 64
	v_lshl_add_u64 v[66:67], v[194:195], 1, s[6:7]
	s_mul_hi_u32 s7, s40, s44
	s_mul_i32 s6, s40, s44
	s_add_i32 s65, s63, 0x400
	s_lshl_b64 s[48:49], s[6:7], 1
	s_mov_b32 m0, s63
	s_waitcnt vmcnt(2)
	s_barrier
	s_add_u32 s6, s79, s48
	global_load_lds_dwordx4 v[66:67], off
	v_lshl_add_u64 v[66:67], v[66:67], 0, s[82:83]
	s_mov_b32 m0, s65
	s_addc_u32 s7, s80, s49
	global_load_lds_dwordx4 v[66:67], off
	v_lshl_add_u64 v[66:67], v[134:135], 1, s[6:7]
	v_lshl_add_u64 v[66:67], v[66:67], 0, s[86:87]
	s_mov_b32 m0, s41
	s_add_i32 s77, s63, 0x8400
	global_load_lds_dwordx4 v[66:67], off
	v_lshl_add_u64 v[66:67], v[136:137], 1, s[6:7]
	v_lshl_add_u64 v[66:67], v[66:67], 0, s[86:87]
	s_mov_b32 m0, s77
	s_sub_i32 s6, s11, 64
	global_load_lds_dwordx4 v[66:67], off
	s_cmp_lg_u32 s11, 0
	s_cselect_b64 s[94:95], -1, 0
	s_cmp_le_i32 s6, s43
	s_cselect_b64 vcc, -1, 0
	s_and_b64 s[94:95], s[94:95], vcc
	s_add_i32 s64, s22, 0xffffff80
	s_cmp_gt_i32 s11, s64
	s_cselect_b64 vcc, -1, 0
	s_and_b64 s[94:95], s[94:95], vcc
	s_andn2_b64 vcc, exec, s[94:95]
	s_cbranch_vccnz .LBB0_384
	s_cmp_gt_i32 s37, -1
	s_cselect_b64 s[94:95], -1, 0
	s_sub_i32 s0, s22, 34
	s_cmp_gt_i32 s11, s0
	s_cselect_b64 vcc, -1, 0
	s_and_b64 s[94:95], s[94:95], vcc
	s_and_b64 vcc, exec, s[94:95]
	ds_read_b128 v[204:207], v163 offset:49152
	ds_read_b128 v[208:211], v164 offset:49152
	ds_read_b128 v[212:215], v165 offset:49152
	ds_read_b128 v[216:219], v166 offset:49152
	ds_read_b128 v[220:223], v163 offset:49280
	ds_read_b128 v[224:227], v164 offset:49280
	ds_read_b128 v[228:231], v165 offset:49280
	ds_read_b128 v[240:243], v166 offset:49280
	ds_read_b128 v[244:247], v163 offset:57344
	ds_read_b128 v[248:251], v164 offset:57344
	ds_read_b128 v[190:193], v165 offset:57344
	s_waitcnt lgkmcnt(10)
	v_mfma_f32_32x32x16_bf16 v[82:97], v[204:207], v[126:129], 0
	s_waitcnt lgkmcnt(9)
	v_mfma_f32_32x32x16_bf16 v[82:97], v[208:211], v[118:121], v[82:97]
	s_waitcnt lgkmcnt(8)
	v_mfma_f32_32x32x16_bf16 v[82:97], v[212:215], v[122:125], v[82:97]
	s_waitcnt lgkmcnt(7)
	v_mfma_f32_32x32x16_bf16 v[82:97], v[216:219], v[114:117], v[82:97]
	s_waitcnt lgkmcnt(6)
	v_mfma_f32_32x32x16_bf16 v[82:97], v[220:223], v[110:113], v[82:97]
	ds_read_b128 v[204:207], v166 offset:57344
	ds_read_b128 v[208:211], v163 offset:57472
	ds_read_b128 v[212:215], v164 offset:57472
	ds_read_b128 v[216:219], v165 offset:57472
	ds_read_b128 v[220:223], v166 offset:57472
	s_waitcnt lgkmcnt(10)
	v_mfma_f32_32x32x16_bf16 v[82:97], v[224:227], v[106:109], v[82:97]
	s_waitcnt lgkmcnt(9)
	v_mfma_f32_32x32x16_bf16 v[82:97], v[228:231], v[102:105], v[82:97]
	s_waitcnt lgkmcnt(8)
	v_mfma_f32_32x32x16_bf16 v[82:97], v[240:243], v[98:101], v[82:97]
	s_waitcnt lgkmcnt(7)
	v_mfma_f32_32x32x16_bf16 v[66:81], v[244:247], v[126:129], 0
	s_waitcnt lgkmcnt(6)
	v_mfma_f32_32x32x16_bf16 v[66:81], v[248:251], v[118:121], v[66:81]
	s_waitcnt lgkmcnt(5)
	v_mfma_f32_32x32x16_bf16 v[66:81], v[190:193], v[122:125], v[66:81]
	s_waitcnt lgkmcnt(4)
	v_mfma_f32_32x32x16_bf16 v[66:81], v[204:207], v[114:117], v[66:81]
	s_waitcnt lgkmcnt(3)
	v_mfma_f32_32x32x16_bf16 v[66:81], v[208:211], v[110:113], v[66:81]
	s_waitcnt lgkmcnt(2)
	v_mfma_f32_32x32x16_bf16 v[66:81], v[212:215], v[106:109], v[66:81]
	s_waitcnt lgkmcnt(1)
	v_mfma_f32_32x32x16_bf16 v[66:81], v[216:219], v[102:105], v[66:81]
	s_waitcnt lgkmcnt(0)
	v_mfma_f32_32x32x16_bf16 v[66:81], v[220:223], v[98:101], v[66:81]
	s_cbranch_vccnz .LBB0_381
	v_subrev_u32_e32 v138, s6, v1
	s_movk_i32 s0, 0x81
	v_cmp_gt_u32_e32 vcc, s0, v138
	v_add_u32_e32 v174, 0xffffff5f, v138
	s_nop 5
	v_cndmask_b32_e32 v82, v234, v82, vcc
	v_cmp_lt_u32_e32 vcc, s69, v174
	v_add_u32_e32 v174, 0xffffff7e, v138
	s_nop 0
	v_cndmask_b32_e32 v66, v234, v66, vcc
	v_cmp_lt_u32_e32 vcc, s69, v174
	v_add_u32_e32 v174, 0xffffff5e, v138
	s_nop 0
	v_cndmask_b32_e32 v83, v234, v83, vcc
	v_cmp_lt_u32_e32 vcc, s69, v174
	v_add_u32_e32 v174, 0xffffff7d, v138
	s_nop 0
	v_cndmask_b32_e32 v67, v234, v67, vcc
	v_cmp_lt_u32_e32 vcc, s69, v174
	v_add_u32_e32 v174, 0xffffff5d, v138
	s_nop 0
	v_cndmask_b32_e32 v84, v234, v84, vcc
	v_cmp_lt_u32_e32 vcc, s69, v174
	v_add_u32_e32 v174, 0xffffff7c, v138
	s_nop 0
	v_cndmask_b32_e32 v68, v234, v68, vcc
	v_cmp_lt_u32_e32 vcc, s69, v174
	v_add_u32_e32 v174, 0xffffff5c, v138
	s_nop 0
	v_cndmask_b32_e32 v85, v234, v85, vcc
	v_cmp_lt_u32_e32 vcc, s69, v174
	v_add_u32_e32 v174, 0xffffff77, v138
	s_nop 0
	v_cndmask_b32_e32 v69, v234, v69, vcc
	v_cmp_lt_u32_e32 vcc, s69, v174
	v_add_u32_e32 v174, 0xffffff57, v138
	s_nop 0
	v_cndmask_b32_e32 v86, v234, v86, vcc
	v_cmp_lt_u32_e32 vcc, s69, v174
	v_add_u32_e32 v174, 0xffffff76, v138
	s_nop 0
	v_cndmask_b32_e32 v70, v234, v70, vcc
	v_cmp_lt_u32_e32 vcc, s69, v174
	v_add_u32_e32 v174, 0xffffff56, v138
	s_nop 0
	v_cndmask_b32_e32 v87, v234, v87, vcc
	v_cmp_lt_u32_e32 vcc, s69, v174
	v_add_u32_e32 v174, 0xffffff75, v138
	s_nop 0
	v_cndmask_b32_e32 v71, v234, v71, vcc
	v_cmp_lt_u32_e32 vcc, s69, v174
	v_add_u32_e32 v174, 0xffffff55, v138
	s_nop 0
	v_cndmask_b32_e32 v88, v234, v88, vcc
	v_cmp_lt_u32_e32 vcc, s69, v174
	v_add_u32_e32 v174, 0xffffff74, v138
	s_nop 0
	v_cndmask_b32_e32 v72, v234, v72, vcc
	v_cmp_lt_u32_e32 vcc, s69, v174
	v_add_u32_e32 v174, 0xffffff54, v138
	s_nop 0
	v_cndmask_b32_e32 v89, v234, v89, vcc
	v_cmp_lt_u32_e32 vcc, s69, v174
	v_add_u32_e32 v174, 0xffffff6f, v138
	s_nop 0
	v_cndmask_b32_e32 v73, v234, v73, vcc
	v_cmp_lt_u32_e32 vcc, s69, v174
	v_add_u32_e32 v174, 0xffffff4f, v138
	s_nop 0
	v_cndmask_b32_e32 v90, v234, v90, vcc
	v_cmp_lt_u32_e32 vcc, s69, v174
	v_add_u32_e32 v174, 0xffffff6e, v138
	s_nop 0
	v_cndmask_b32_e32 v74, v234, v74, vcc
	v_cmp_lt_u32_e32 vcc, s69, v174
	v_add_u32_e32 v174, 0xffffff4e, v138
	s_nop 0
	v_cndmask_b32_e32 v91, v234, v91, vcc
	v_cmp_lt_u32_e32 vcc, s69, v174
	v_add_u32_e32 v174, 0xffffff6d, v138
	s_nop 0
	v_cndmask_b32_e32 v75, v234, v75, vcc
	v_cmp_lt_u32_e32 vcc, s69, v174
	v_add_u32_e32 v174, 0xffffff4d, v138
	s_nop 0
	v_cndmask_b32_e32 v92, v234, v92, vcc
	v_cmp_lt_u32_e32 vcc, s69, v174
	v_add_u32_e32 v174, 0xffffff6c, v138
	s_nop 0
	v_cndmask_b32_e32 v76, v234, v76, vcc
	v_cmp_lt_u32_e32 vcc, s69, v174
	v_add_u32_e32 v174, 0xffffff4c, v138
	s_nop 0
	v_cndmask_b32_e32 v93, v234, v93, vcc
	v_cmp_lt_u32_e32 vcc, s69, v174
	v_add_u32_e32 v174, 0xffffff67, v138
	s_nop 0
	v_cndmask_b32_e32 v77, v234, v77, vcc
	v_cmp_lt_u32_e32 vcc, s69, v174
	v_add_u32_e32 v174, 0xffffff47, v138
	s_nop 0
	v_cndmask_b32_e32 v94, v234, v94, vcc
	v_cmp_lt_u32_e32 vcc, s69, v174
	v_add_u32_e32 v174, 0xffffff66, v138
	s_nop 0
	v_cndmask_b32_e32 v78, v234, v78, vcc
	v_cmp_lt_u32_e32 vcc, s69, v174
	v_add_u32_e32 v174, 0xffffff46, v138
	s_nop 0
	v_cndmask_b32_e32 v95, v234, v95, vcc
	v_cmp_lt_u32_e32 vcc, s69, v174
	v_add_u32_e32 v174, 0xffffff65, v138
	s_nop 0
	v_cndmask_b32_e32 v79, v234, v79, vcc
	v_cmp_lt_u32_e32 vcc, s69, v174
	v_add_u32_e32 v174, 0xffffff45, v138
	s_nop 0
	v_cndmask_b32_e32 v96, v234, v96, vcc
	v_cmp_lt_u32_e32 vcc, s69, v174
	v_add_u32_e32 v174, 0xffffff64, v138
	v_add_u32_e32 v138, 0xffffff44, v138
	v_cndmask_b32_e32 v80, v234, v80, vcc
	v_cmp_lt_u32_e32 vcc, s69, v174
	s_nop 1
	v_cndmask_b32_e32 v97, v234, v97, vcc
	v_cmp_lt_u32_e32 vcc, s69, v138
	s_nop 1
	v_cndmask_b32_e32 v81, v234, v81, vcc

.LBB0_384:
	s_add_u32 s6, s67, s48
	s_addc_u32 s7, s68, s49
	s_or_b32 s58, s11, 0x80
	v_lshl_add_u64 v[66:67], v[194:195], 1, s[6:7]
	s_mul_hi_u32 s7, s40, s58
	s_mul_i32 s6, s40, s58
	s_lshl_b64 s[48:49], s[6:7], 1
	s_mov_b32 m0, s71
	s_waitcnt vmcnt(2)
	s_barrier
	s_add_u32 s6, s79, s48
	global_load_lds_dwordx4 v[66:67], off
	v_lshl_add_u64 v[66:67], v[66:67], 0, s[82:83]
	s_mov_b32 m0, s70
	s_addc_u32 s7, s80, s49
	global_load_lds_dwordx4 v[66:67], off
	s_add_i32 s57, s63, 0xc000
	v_lshl_add_u64 v[66:67], v[134:135], 1, s[6:7]
	v_lshl_add_u64 v[66:67], v[66:67], 0, s[86:87]
	s_mov_b32 m0, s57
	s_add_i32 s76, s63, 0xc400
	global_load_lds_dwordx4 v[66:67], off
	v_lshl_add_u64 v[66:67], v[136:137], 1, s[6:7]
	v_lshl_add_u64 v[66:67], v[66:67], 0, s[86:87]
	s_mov_b32 m0, s76
	s_cmp_gt_i32 s11, s43
	global_load_lds_dwordx4 v[66:67], off
	s_cselect_b64 s[6:7], -1, 0
	s_or_b32 s0, s11, 63
	s_cmp_lt_i32 s0, s64
	s_cselect_b64 s[94:95], -1, 0
	s_or_b64 s[6:7], s[6:7], s[94:95]
	s_and_b64 vcc, exec, s[6:7]
	s_cbranch_vccnz .LBB0_390
	s_cmp_gt_i32 s37, 1
	s_cselect_b64 s[6:7], -1, 0
	s_add_i32 s0, s22, 0xffffff9e
	s_cmp_gt_i32 s11, s0
	s_cselect_b64 s[94:95], -1, 0
	s_and_b64 s[6:7], s[6:7], s[94:95]
	s_and_b64 vcc, exec, s[6:7]
	ds_read_b128 v[204:207], v167
	ds_read_b128 v[208:211], v168
	ds_read_b128 v[212:215], v169
	ds_read_b128 v[216:219], v170
	ds_read_b128 v[220:223], v167 offset:128
	ds_read_b128 v[224:227], v168 offset:128
	ds_read_b128 v[228:231], v169 offset:128
	ds_read_b128 v[240:243], v170 offset:128
	ds_read_b128 v[244:247], v167 offset:8192
	ds_read_b128 v[248:251], v168 offset:8192
	ds_read_b128 v[190:193], v169 offset:8192
	s_waitcnt lgkmcnt(10)
	v_mfma_f32_32x32x16_bf16 v[82:97], v[204:207], v[126:129], 0
	s_waitcnt lgkmcnt(9)
	v_mfma_f32_32x32x16_bf16 v[82:97], v[208:211], v[118:121], v[82:97]
	s_waitcnt lgkmcnt(8)
	v_mfma_f32_32x32x16_bf16 v[82:97], v[212:215], v[122:125], v[82:97]
	s_waitcnt lgkmcnt(7)
	v_mfma_f32_32x32x16_bf16 v[82:97], v[216:219], v[114:117], v[82:97]
	s_waitcnt lgkmcnt(6)
	v_mfma_f32_32x32x16_bf16 v[82:97], v[220:223], v[110:113], v[82:97]
	ds_read_b128 v[204:207], v170 offset:8192
	ds_read_b128 v[208:211], v167 offset:8320
	ds_read_b128 v[212:215], v168 offset:8320
	ds_read_b128 v[216:219], v169 offset:8320
	ds_read_b128 v[220:223], v170 offset:8320
	s_waitcnt lgkmcnt(10)
	v_mfma_f32_32x32x16_bf16 v[82:97], v[224:227], v[106:109], v[82:97]
	s_waitcnt lgkmcnt(9)
	v_mfma_f32_32x32x16_bf16 v[82:97], v[228:231], v[102:105], v[82:97]
	s_waitcnt lgkmcnt(8)
	v_mfma_f32_32x32x16_bf16 v[82:97], v[240:243], v[98:101], v[82:97]
	s_waitcnt lgkmcnt(7)
	v_mfma_f32_32x32x16_bf16 v[66:81], v[244:247], v[126:129], 0
	s_waitcnt lgkmcnt(6)
	v_mfma_f32_32x32x16_bf16 v[66:81], v[248:251], v[118:121], v[66:81]
	s_waitcnt lgkmcnt(5)
	v_mfma_f32_32x32x16_bf16 v[66:81], v[190:193], v[122:125], v[66:81]
	s_waitcnt lgkmcnt(4)
	v_mfma_f32_32x32x16_bf16 v[66:81], v[204:207], v[114:117], v[66:81]
	s_waitcnt lgkmcnt(3)
	v_mfma_f32_32x32x16_bf16 v[66:81], v[208:211], v[110:113], v[66:81]
	s_waitcnt lgkmcnt(2)
	v_mfma_f32_32x32x16_bf16 v[66:81], v[212:215], v[106:109], v[66:81]
	s_waitcnt lgkmcnt(1)
	v_mfma_f32_32x32x16_bf16 v[66:81], v[216:219], v[102:105], v[66:81]
	s_waitcnt lgkmcnt(0)
	v_mfma_f32_32x32x16_bf16 v[66:81], v[220:223], v[98:101], v[66:81]
	s_cbranch_vccnz .LBB0_387
	v_subrev_u32_e32 v138, s11, v1
	s_movk_i32 s0, 0x81
	v_cmp_gt_u32_e32 vcc, s0, v138
	v_add_u32_e32 v174, 0xffffff5f, v138
	s_nop 5
	v_cndmask_b32_e32 v82, v234, v82, vcc
	v_cmp_lt_u32_e32 vcc, s69, v174
	v_add_u32_e32 v174, 0xffffff7e, v138
	s_nop 0
	v_cndmask_b32_e32 v66, v234, v66, vcc
	v_cmp_lt_u32_e32 vcc, s69, v174
	v_add_u32_e32 v174, 0xffffff5e, v138
	s_nop 0
	v_cndmask_b32_e32 v83, v234, v83, vcc
	v_cmp_lt_u32_e32 vcc, s69, v174
	v_add_u32_e32 v174, 0xffffff7d, v138
	s_nop 0
	v_cndmask_b32_e32 v67, v234, v67, vcc
	v_cmp_lt_u32_e32 vcc, s69, v174
	v_add_u32_e32 v174, 0xffffff5d, v138
	s_nop 0
	v_cndmask_b32_e32 v84, v234, v84, vcc
	v_cmp_lt_u32_e32 vcc, s69, v174
	v_add_u32_e32 v174, 0xffffff7c, v138
	s_nop 0
	v_cndmask_b32_e32 v68, v234, v68, vcc
	v_cmp_lt_u32_e32 vcc, s69, v174
	v_add_u32_e32 v174, 0xffffff5c, v138
	s_nop 0
	v_cndmask_b32_e32 v85, v234, v85, vcc
	v_cmp_lt_u32_e32 vcc, s69, v174
	v_add_u32_e32 v174, 0xffffff77, v138
	s_nop 0
	v_cndmask_b32_e32 v69, v234, v69, vcc
	v_cmp_lt_u32_e32 vcc, s69, v174
	v_add_u32_e32 v174, 0xffffff57, v138
	s_nop 0
	v_cndmask_b32_e32 v86, v234, v86, vcc
	v_cmp_lt_u32_e32 vcc, s69, v174
	v_add_u32_e32 v174, 0xffffff76, v138
	s_nop 0
	v_cndmask_b32_e32 v70, v234, v70, vcc
	v_cmp_lt_u32_e32 vcc, s69, v174
	v_add_u32_e32 v174, 0xffffff56, v138
	s_nop 0
	v_cndmask_b32_e32 v87, v234, v87, vcc
	v_cmp_lt_u32_e32 vcc, s69, v174
	v_add_u32_e32 v174, 0xffffff75, v138
	s_nop 0
	v_cndmask_b32_e32 v71, v234, v71, vcc
	v_cmp_lt_u32_e32 vcc, s69, v174
	v_add_u32_e32 v174, 0xffffff55, v138
	s_nop 0
	v_cndmask_b32_e32 v88, v234, v88, vcc
	v_cmp_lt_u32_e32 vcc, s69, v174
	v_add_u32_e32 v174, 0xffffff74, v138
	s_nop 0
	v_cndmask_b32_e32 v72, v234, v72, vcc
	v_cmp_lt_u32_e32 vcc, s69, v174
	v_add_u32_e32 v174, 0xffffff54, v138
	s_nop 0
	v_cndmask_b32_e32 v89, v234, v89, vcc
	v_cmp_lt_u32_e32 vcc, s69, v174
	v_add_u32_e32 v174, 0xffffff6f, v138
	s_nop 0
	v_cndmask_b32_e32 v73, v234, v73, vcc
	v_cmp_lt_u32_e32 vcc, s69, v174
	v_add_u32_e32 v174, 0xffffff4f, v138
	s_nop 0
	v_cndmask_b32_e32 v90, v234, v90, vcc
	v_cmp_lt_u32_e32 vcc, s69, v174
	v_add_u32_e32 v174, 0xffffff6e, v138
	s_nop 0
	v_cndmask_b32_e32 v74, v234, v74, vcc
	v_cmp_lt_u32_e32 vcc, s69, v174
	v_add_u32_e32 v174, 0xffffff4e, v138
	s_nop 0
	v_cndmask_b32_e32 v91, v234, v91, vcc
	v_cmp_lt_u32_e32 vcc, s69, v174
	v_add_u32_e32 v174, 0xffffff6d, v138
	s_nop 0
	v_cndmask_b32_e32 v75, v234, v75, vcc
	v_cmp_lt_u32_e32 vcc, s69, v174
	v_add_u32_e32 v174, 0xffffff4d, v138
	s_nop 0
	v_cndmask_b32_e32 v92, v234, v92, vcc
	v_cmp_lt_u32_e32 vcc, s69, v174
	v_add_u32_e32 v174, 0xffffff6c, v138
	s_nop 0
	v_cndmask_b32_e32 v76, v234, v76, vcc
	v_cmp_lt_u32_e32 vcc, s69, v174
	v_add_u32_e32 v174, 0xffffff4c, v138
	s_nop 0
	v_cndmask_b32_e32 v93, v234, v93, vcc
	v_cmp_lt_u32_e32 vcc, s69, v174
	v_add_u32_e32 v174, 0xffffff67, v138
	s_nop 0
	v_cndmask_b32_e32 v77, v234, v77, vcc
	v_cmp_lt_u32_e32 vcc, s69, v174
	v_add_u32_e32 v174, 0xffffff47, v138
	s_nop 0
	v_cndmask_b32_e32 v94, v234, v94, vcc
	v_cmp_lt_u32_e32 vcc, s69, v174
	v_add_u32_e32 v174, 0xffffff66, v138
	s_nop 0
	v_cndmask_b32_e32 v78, v234, v78, vcc
	v_cmp_lt_u32_e32 vcc, s69, v174
	v_add_u32_e32 v174, 0xffffff46, v138
	s_nop 0
	v_cndmask_b32_e32 v95, v234, v95, vcc
	v_cmp_lt_u32_e32 vcc, s69, v174
	v_add_u32_e32 v174, 0xffffff65, v138
	s_nop 0
	v_cndmask_b32_e32 v79, v234, v79, vcc
	v_cmp_lt_u32_e32 vcc, s69, v174
	v_add_u32_e32 v174, 0xffffff45, v138
	s_nop 0
	v_cndmask_b32_e32 v96, v234, v96, vcc
	v_cmp_lt_u32_e32 vcc, s69, v174
	v_add_u32_e32 v174, 0xffffff64, v138
	v_add_u32_e32 v138, 0xffffff44, v138
	v_cndmask_b32_e32 v80, v234, v80, vcc
	v_cmp_lt_u32_e32 vcc, s69, v174
	s_nop 1
	v_cndmask_b32_e32 v97, v234, v97, vcc
	v_cmp_lt_u32_e32 vcc, s69, v138
	s_nop 1
	v_cndmask_b32_e32 v81, v234, v81, vcc

.LBB0_390:
	s_add_u32 s6, s67, s48
	s_addc_u32 s7, s68, s49
	s_or_b32 s43, s11, 0xc0
	v_lshl_add_u64 v[66:67], v[194:195], 1, s[6:7]
	s_mul_hi_u32 s7, s40, s43
	s_mul_i32 s6, s40, s43
	s_lshl_b64 s[48:49], s[6:7], 1
	s_mov_b32 m0, s63
	s_waitcnt vmcnt(2)
	s_barrier
	s_add_u32 s6, s79, s48
	global_load_lds_dwordx4 v[66:67], off
	v_lshl_add_u64 v[66:67], v[66:67], 0, s[82:83]
	s_mov_b32 m0, s65
	s_addc_u32 s7, s80, s49
	global_load_lds_dwordx4 v[66:67], off
	v_lshl_add_u64 v[66:67], v[134:135], 1, s[6:7]
	v_lshl_add_u64 v[66:67], v[66:67], 0, s[86:87]
	s_add_i32 m0, s41, 0x8000
	s_nop 0
	global_load_lds_dwordx4 v[66:67], off
	v_lshl_add_u64 v[66:67], v[136:137], 1, s[6:7]
	v_lshl_add_u64 v[66:67], v[66:67], 0, s[86:87]
	s_add_i32 m0, s41, 0x8400
	s_cmp_lt_i32 s37, 2
	global_load_lds_dwordx4 v[66:67], off
	s_cselect_b64 s[6:7], -1, 0
	s_or_b32 s0, s11, 0x7f
	s_cmp_lt_i32 s0, s64
	s_cselect_b64 s[94:95], -1, 0
	s_or_b64 s[6:7], s[6:7], s[94:95]
	s_and_b64 vcc, exec, s[6:7]
	s_cbranch_vccnz .LBB0_396
	s_cmp_gt_u32 s37, 3
	s_cselect_b64 s[6:7], -1, 0
	s_add_i32 s0, s22, 0xffffff9e
	s_cmp_gt_i32 s44, s0
	s_cselect_b64 s[94:95], -1, 0
	s_and_b64 s[6:7], s[6:7], s[94:95]
	s_and_b64 vcc, exec, s[6:7]
	ds_read_b128 v[204:207], v163 offset:32768
	ds_read_b128 v[208:211], v164 offset:32768
	ds_read_b128 v[212:215], v165 offset:32768
	ds_read_b128 v[216:219], v166 offset:32768
	ds_read_b128 v[220:223], v163 offset:32896
	ds_read_b128 v[224:227], v164 offset:32896
	ds_read_b128 v[228:231], v165 offset:32896
	ds_read_b128 v[240:243], v166 offset:32896
	ds_read_b128 v[244:247], v163 offset:40960
	ds_read_b128 v[248:251], v164 offset:40960
	ds_read_b128 v[190:193], v165 offset:40960
	s_waitcnt lgkmcnt(10)
	v_mfma_f32_32x32x16_bf16 v[82:97], v[204:207], v[126:129], 0
	s_waitcnt lgkmcnt(9)
	v_mfma_f32_32x32x16_bf16 v[82:97], v[208:211], v[118:121], v[82:97]
	s_waitcnt lgkmcnt(8)
	v_mfma_f32_32x32x16_bf16 v[82:97], v[212:215], v[122:125], v[82:97]
	s_waitcnt lgkmcnt(7)
	v_mfma_f32_32x32x16_bf16 v[82:97], v[216:219], v[114:117], v[82:97]
	s_waitcnt lgkmcnt(6)
	v_mfma_f32_32x32x16_bf16 v[82:97], v[220:223], v[110:113], v[82:97]
	ds_read_b128 v[204:207], v166 offset:40960
	ds_read_b128 v[208:211], v163 offset:41088
	ds_read_b128 v[212:215], v164 offset:41088
	ds_read_b128 v[216:219], v165 offset:41088
	ds_read_b128 v[220:223], v166 offset:41088
	s_waitcnt lgkmcnt(10)
	v_mfma_f32_32x32x16_bf16 v[82:97], v[224:227], v[106:109], v[82:97]
	s_waitcnt lgkmcnt(9)
	v_mfma_f32_32x32x16_bf16 v[82:97], v[228:231], v[102:105], v[82:97]
	s_waitcnt lgkmcnt(8)
	v_mfma_f32_32x32x16_bf16 v[82:97], v[240:243], v[98:101], v[82:97]
	s_waitcnt lgkmcnt(7)
	v_mfma_f32_32x32x16_bf16 v[66:81], v[244:247], v[126:129], 0
	s_waitcnt lgkmcnt(6)
	v_mfma_f32_32x32x16_bf16 v[66:81], v[248:251], v[118:121], v[66:81]
	s_waitcnt lgkmcnt(5)
	v_mfma_f32_32x32x16_bf16 v[66:81], v[190:193], v[122:125], v[66:81]
	s_waitcnt lgkmcnt(4)
	v_mfma_f32_32x32x16_bf16 v[66:81], v[204:207], v[114:117], v[66:81]
	s_waitcnt lgkmcnt(3)
	v_mfma_f32_32x32x16_bf16 v[66:81], v[208:211], v[110:113], v[66:81]
	s_waitcnt lgkmcnt(2)
	v_mfma_f32_32x32x16_bf16 v[66:81], v[212:215], v[106:109], v[66:81]
	s_waitcnt lgkmcnt(1)
	v_mfma_f32_32x32x16_bf16 v[66:81], v[216:219], v[102:105], v[66:81]
	s_waitcnt lgkmcnt(0)
	v_mfma_f32_32x32x16_bf16 v[66:81], v[220:223], v[98:101], v[66:81]
	s_cbranch_vccnz .LBB0_393
	v_subrev_u32_e32 v134, s44, v1
	s_movk_i32 s0, 0x81
	v_cmp_gt_u32_e32 vcc, s0, v134
	v_add_u32_e32 v135, 0xffffff5f, v134
	s_nop 5
	v_cndmask_b32_e32 v82, v234, v82, vcc
	v_cmp_lt_u32_e32 vcc, s69, v135
	v_add_u32_e32 v135, 0xffffff7e, v134
	s_nop 0
	v_cndmask_b32_e32 v66, v234, v66, vcc
	v_cmp_lt_u32_e32 vcc, s69, v135
	v_add_u32_e32 v135, 0xffffff5e, v134
	s_nop 0
	v_cndmask_b32_e32 v83, v234, v83, vcc
	v_cmp_lt_u32_e32 vcc, s69, v135
	v_add_u32_e32 v135, 0xffffff7d, v134
	s_nop 0
	v_cndmask_b32_e32 v67, v234, v67, vcc
	v_cmp_lt_u32_e32 vcc, s69, v135
	v_add_u32_e32 v135, 0xffffff5d, v134
	s_nop 0
	v_cndmask_b32_e32 v84, v234, v84, vcc
	v_cmp_lt_u32_e32 vcc, s69, v135
	v_add_u32_e32 v135, 0xffffff7c, v134
	s_nop 0
	v_cndmask_b32_e32 v68, v234, v68, vcc
	v_cmp_lt_u32_e32 vcc, s69, v135
	v_add_u32_e32 v135, 0xffffff5c, v134
	s_nop 0
	v_cndmask_b32_e32 v85, v234, v85, vcc
	v_cmp_lt_u32_e32 vcc, s69, v135
	v_add_u32_e32 v135, 0xffffff77, v134
	s_nop 0
	v_cndmask_b32_e32 v69, v234, v69, vcc
	v_cmp_lt_u32_e32 vcc, s69, v135
	v_add_u32_e32 v135, 0xffffff57, v134
	s_nop 0
	v_cndmask_b32_e32 v86, v234, v86, vcc
	v_cmp_lt_u32_e32 vcc, s69, v135
	v_add_u32_e32 v135, 0xffffff76, v134
	s_nop 0
	v_cndmask_b32_e32 v70, v234, v70, vcc
	v_cmp_lt_u32_e32 vcc, s69, v135
	v_add_u32_e32 v135, 0xffffff56, v134
	s_nop 0
	v_cndmask_b32_e32 v87, v234, v87, vcc
	v_cmp_lt_u32_e32 vcc, s69, v135
	v_add_u32_e32 v135, 0xffffff75, v134
	s_nop 0
	v_cndmask_b32_e32 v71, v234, v71, vcc
	v_cmp_lt_u32_e32 vcc, s69, v135
	v_add_u32_e32 v135, 0xffffff55, v134
	s_nop 0
	v_cndmask_b32_e32 v88, v234, v88, vcc
	v_cmp_lt_u32_e32 vcc, s69, v135
	v_add_u32_e32 v135, 0xffffff74, v134
	s_nop 0
	v_cndmask_b32_e32 v72, v234, v72, vcc
	v_cmp_lt_u32_e32 vcc, s69, v135
	v_add_u32_e32 v135, 0xffffff54, v134
	s_nop 0
	v_cndmask_b32_e32 v89, v234, v89, vcc
	v_cmp_lt_u32_e32 vcc, s69, v135
	v_add_u32_e32 v135, 0xffffff6f, v134
	s_nop 0
	v_cndmask_b32_e32 v73, v234, v73, vcc
	v_cmp_lt_u32_e32 vcc, s69, v135
	v_add_u32_e32 v135, 0xffffff4f, v134
	s_nop 0
	v_cndmask_b32_e32 v90, v234, v90, vcc
	v_cmp_lt_u32_e32 vcc, s69, v135
	v_add_u32_e32 v135, 0xffffff6e, v134
	s_nop 0
	v_cndmask_b32_e32 v74, v234, v74, vcc
	v_cmp_lt_u32_e32 vcc, s69, v135
	v_add_u32_e32 v135, 0xffffff4e, v134
	s_nop 0
	v_cndmask_b32_e32 v91, v234, v91, vcc
	v_cmp_lt_u32_e32 vcc, s69, v135
	v_add_u32_e32 v135, 0xffffff6d, v134
	s_nop 0
	v_cndmask_b32_e32 v75, v234, v75, vcc
	v_cmp_lt_u32_e32 vcc, s69, v135
	v_add_u32_e32 v135, 0xffffff4d, v134
	s_nop 0
	v_cndmask_b32_e32 v92, v234, v92, vcc
	v_cmp_lt_u32_e32 vcc, s69, v135
	v_add_u32_e32 v135, 0xffffff6c, v134
	s_nop 0
	v_cndmask_b32_e32 v76, v234, v76, vcc
	v_cmp_lt_u32_e32 vcc, s69, v135
	v_add_u32_e32 v135, 0xffffff4c, v134
	s_nop 0
	v_cndmask_b32_e32 v93, v234, v93, vcc
	v_cmp_lt_u32_e32 vcc, s69, v135
	v_add_u32_e32 v135, 0xffffff67, v134
	s_nop 0
	v_cndmask_b32_e32 v77, v234, v77, vcc
	v_cmp_lt_u32_e32 vcc, s69, v135
	v_add_u32_e32 v135, 0xffffff47, v134
	s_nop 0
	v_cndmask_b32_e32 v94, v234, v94, vcc
	v_cmp_lt_u32_e32 vcc, s69, v135
	v_add_u32_e32 v135, 0xffffff66, v134
	s_nop 0
	v_cndmask_b32_e32 v78, v234, v78, vcc
	v_cmp_lt_u32_e32 vcc, s69, v135
	v_add_u32_e32 v135, 0xffffff46, v134
	s_nop 0
	v_cndmask_b32_e32 v95, v234, v95, vcc
	v_cmp_lt_u32_e32 vcc, s69, v135
	v_add_u32_e32 v135, 0xffffff65, v134
	s_nop 0
	v_cndmask_b32_e32 v79, v234, v79, vcc
	v_cmp_lt_u32_e32 vcc, s69, v135
	v_add_u32_e32 v135, 0xffffff45, v134
	s_nop 0
	v_cndmask_b32_e32 v96, v234, v96, vcc
	v_cmp_lt_u32_e32 vcc, s69, v135
	v_add_u32_e32 v135, 0xffffff64, v134
	v_add_u32_e32 v134, 0xffffff44, v134
	v_cndmask_b32_e32 v80, v234, v80, vcc
	v_cmp_lt_u32_e32 vcc, s69, v135
	s_nop 1
	v_cndmask_b32_e32 v97, v234, v97, vcc
	v_cmp_lt_u32_e32 vcc, s69, v134
	s_nop 1
	v_cndmask_b32_e32 v81, v234, v81, vcc

.LBB0_396:
	s_add_u32 s6, s67, s48
	s_addc_u32 s7, s68, s49
	s_mul_i32 s1, s28, 0x2c00
	s_mul_hi_i32 s0, s28, 0x2c00
	s_add_u32 s1, s52, s1
	v_lshl_add_u64 v[66:67], v[194:195], 1, s[6:7]
	s_addc_u32 s0, s53, s0
	s_lshl_b32 s6, s50, 7
	s_ashr_i32 s7, s6, 31
	s_lshl_b64 s[6:7], s[6:7], 1
	s_add_u32 s44, s1, s6
	s_addc_u32 s67, s0, s7
	s_max_i32 s0, s29, 0x80
	s_mul_i32 s40, s31, 0x1600
	s_addk_i32 s0, 0xff80
	s_mov_b32 m0, s71
	s_waitcnt vmcnt(2)
	s_barrier
	s_mul_hi_u32 s7, s0, s40
	s_mul_i32 s6, s0, s40
	global_load_lds_dwordx4 v[66:67], off
	v_lshl_add_u64 v[66:67], v[66:67], 0, s[82:83]
	s_mov_b32 m0, s70
	s_lshl_b64 s[48:49], s[6:7], 1
	global_load_lds_dwordx4 v[66:67], off
	s_add_u32 s6, s44, s48
	v_mul_lo_u32 v66, v173, s40
	s_addc_u32 s7, s67, s49
	v_or_b32_e32 v194, v66, v145
	v_lshl_add_u64 v[66:67], v[194:195], 1, s[6:7]
	v_lshl_add_u64 v[66:67], v[66:67], 0, s[86:87]
	s_mov_b32 m0, s41
	v_mov_b32_e32 v135, v195
	global_load_lds_dwordx4 v[66:67], off
	v_mul_lo_u32 v66, v172, s40
	v_or_b32_e32 v134, v162, v66
	v_lshl_add_u64 v[66:67], v[134:135], 1, s[6:7]
	v_lshl_add_u64 v[66:67], v[66:67], 0, s[86:87]
	s_mov_b32 m0, s77
	s_cmp_lt_i32 s37, 4
	global_load_lds_dwordx4 v[66:67], off
	s_cselect_b64 s[6:7], -1, 0
	s_or_b32 s0, s11, 0xbf
	s_cmp_lt_i32 s0, s64
	s_cselect_b64 s[70:71], -1, 0
	s_or_b64 s[6:7], s[6:7], s[70:71]
	s_and_b64 vcc, exec, s[6:7]
	s_cbranch_vccnz .LBB0_402
	s_cmp_gt_u32 s37, 5
	s_cselect_b64 s[6:7], -1, 0
	s_add_i32 s0, s22, 0xffffff9e
	s_cmp_gt_i32 s58, s0
	s_cselect_b64 s[70:71], -1, 0
	s_and_b64 s[6:7], s[6:7], s[70:71]
	s_and_b64 vcc, exec, s[6:7]
	ds_read_b128 v[204:207], v163 offset:49152
	ds_read_b128 v[208:211], v164 offset:49152
	ds_read_b128 v[212:215], v165 offset:49152
	ds_read_b128 v[216:219], v166 offset:49152
	ds_read_b128 v[220:223], v163 offset:49280
	ds_read_b128 v[224:227], v164 offset:49280
	ds_read_b128 v[228:231], v165 offset:49280
	ds_read_b128 v[240:243], v166 offset:49280
	ds_read_b128 v[244:247], v163 offset:57344
	ds_read_b128 v[248:251], v164 offset:57344
	ds_read_b128 v[190:193], v165 offset:57344
	s_waitcnt lgkmcnt(10)
	v_mfma_f32_32x32x16_bf16 v[82:97], v[204:207], v[126:129], 0
	s_waitcnt lgkmcnt(9)
	v_mfma_f32_32x32x16_bf16 v[82:97], v[208:211], v[118:121], v[82:97]
	s_waitcnt lgkmcnt(8)
	v_mfma_f32_32x32x16_bf16 v[82:97], v[212:215], v[122:125], v[82:97]
	s_waitcnt lgkmcnt(7)
	v_mfma_f32_32x32x16_bf16 v[82:97], v[216:219], v[114:117], v[82:97]
	s_waitcnt lgkmcnt(6)
	v_mfma_f32_32x32x16_bf16 v[82:97], v[220:223], v[110:113], v[82:97]
	ds_read_b128 v[204:207], v166 offset:57344
	ds_read_b128 v[208:211], v163 offset:57472
	ds_read_b128 v[212:215], v164 offset:57472
	ds_read_b128 v[216:219], v165 offset:57472
	ds_read_b128 v[220:223], v166 offset:57472
	s_waitcnt lgkmcnt(10)
	v_mfma_f32_32x32x16_bf16 v[82:97], v[224:227], v[106:109], v[82:97]
	s_waitcnt lgkmcnt(9)
	v_mfma_f32_32x32x16_bf16 v[82:97], v[228:231], v[102:105], v[82:97]
	s_waitcnt lgkmcnt(8)
	v_mfma_f32_32x32x16_bf16 v[82:97], v[240:243], v[98:101], v[82:97]
	s_waitcnt lgkmcnt(7)
	v_mfma_f32_32x32x16_bf16 v[66:81], v[244:247], v[126:129], 0
	s_waitcnt lgkmcnt(6)
	v_mfma_f32_32x32x16_bf16 v[66:81], v[248:251], v[118:121], v[66:81]
	s_waitcnt lgkmcnt(5)
	v_mfma_f32_32x32x16_bf16 v[66:81], v[190:193], v[122:125], v[66:81]
	s_waitcnt lgkmcnt(4)
	v_mfma_f32_32x32x16_bf16 v[66:81], v[204:207], v[114:117], v[66:81]
	s_waitcnt lgkmcnt(3)
	v_mfma_f32_32x32x16_bf16 v[66:81], v[208:211], v[110:113], v[66:81]
	s_waitcnt lgkmcnt(2)
	v_mfma_f32_32x32x16_bf16 v[66:81], v[212:215], v[106:109], v[66:81]
	s_waitcnt lgkmcnt(1)
	v_mfma_f32_32x32x16_bf16 v[66:81], v[216:219], v[102:105], v[66:81]
	s_waitcnt lgkmcnt(0)
	v_mfma_f32_32x32x16_bf16 v[66:81], v[220:223], v[98:101], v[66:81]
	s_cbranch_vccnz .LBB0_399
	v_subrev_u32_e32 v136, s58, v1
	s_movk_i32 s0, 0x81
	v_cmp_gt_u32_e32 vcc, s0, v136
	v_add_u32_e32 v137, 0xffffff5f, v136
	s_nop 5
	v_cndmask_b32_e32 v82, v234, v82, vcc
	v_cmp_lt_u32_e32 vcc, s69, v137
	v_add_u32_e32 v137, 0xffffff7e, v136
	s_nop 0
	v_cndmask_b32_e32 v66, v234, v66, vcc
	v_cmp_lt_u32_e32 vcc, s69, v137
	v_add_u32_e32 v137, 0xffffff5e, v136
	s_nop 0
	v_cndmask_b32_e32 v83, v234, v83, vcc
	v_cmp_lt_u32_e32 vcc, s69, v137
	v_add_u32_e32 v137, 0xffffff7d, v136
	s_nop 0
	v_cndmask_b32_e32 v67, v234, v67, vcc
	v_cmp_lt_u32_e32 vcc, s69, v137
	v_add_u32_e32 v137, 0xffffff5d, v136
	s_nop 0
	v_cndmask_b32_e32 v84, v234, v84, vcc
	v_cmp_lt_u32_e32 vcc, s69, v137
	v_add_u32_e32 v137, 0xffffff7c, v136
	s_nop 0
	v_cndmask_b32_e32 v68, v234, v68, vcc
	v_cmp_lt_u32_e32 vcc, s69, v137
	v_add_u32_e32 v137, 0xffffff5c, v136
	s_nop 0
	v_cndmask_b32_e32 v85, v234, v85, vcc
	v_cmp_lt_u32_e32 vcc, s69, v137
	v_add_u32_e32 v137, 0xffffff77, v136
	s_nop 0
	v_cndmask_b32_e32 v69, v234, v69, vcc
	v_cmp_lt_u32_e32 vcc, s69, v137
	v_add_u32_e32 v137, 0xffffff57, v136
	s_nop 0
	v_cndmask_b32_e32 v86, v234, v86, vcc
	v_cmp_lt_u32_e32 vcc, s69, v137
	v_add_u32_e32 v137, 0xffffff76, v136
	s_nop 0
	v_cndmask_b32_e32 v70, v234, v70, vcc
	v_cmp_lt_u32_e32 vcc, s69, v137
	v_add_u32_e32 v137, 0xffffff56, v136
	s_nop 0
	v_cndmask_b32_e32 v87, v234, v87, vcc
	v_cmp_lt_u32_e32 vcc, s69, v137
	v_add_u32_e32 v137, 0xffffff75, v136
	s_nop 0
	v_cndmask_b32_e32 v71, v234, v71, vcc
	v_cmp_lt_u32_e32 vcc, s69, v137
	v_add_u32_e32 v137, 0xffffff55, v136
	s_nop 0
	v_cndmask_b32_e32 v88, v234, v88, vcc
	v_cmp_lt_u32_e32 vcc, s69, v137
	v_add_u32_e32 v137, 0xffffff74, v136
	s_nop 0
	v_cndmask_b32_e32 v72, v234, v72, vcc
	v_cmp_lt_u32_e32 vcc, s69, v137
	v_add_u32_e32 v137, 0xffffff54, v136
	s_nop 0
	v_cndmask_b32_e32 v89, v234, v89, vcc
	v_cmp_lt_u32_e32 vcc, s69, v137
	v_add_u32_e32 v137, 0xffffff6f, v136
	s_nop 0
	v_cndmask_b32_e32 v73, v234, v73, vcc
	v_cmp_lt_u32_e32 vcc, s69, v137
	v_add_u32_e32 v137, 0xffffff4f, v136
	s_nop 0
	v_cndmask_b32_e32 v90, v234, v90, vcc
	v_cmp_lt_u32_e32 vcc, s69, v137
	v_add_u32_e32 v137, 0xffffff6e, v136
	s_nop 0
	v_cndmask_b32_e32 v74, v234, v74, vcc
	v_cmp_lt_u32_e32 vcc, s69, v137
	v_add_u32_e32 v137, 0xffffff4e, v136
	s_nop 0
	v_cndmask_b32_e32 v91, v234, v91, vcc
	v_cmp_lt_u32_e32 vcc, s69, v137
	v_add_u32_e32 v137, 0xffffff6d, v136
	s_nop 0
	v_cndmask_b32_e32 v75, v234, v75, vcc
	v_cmp_lt_u32_e32 vcc, s69, v137
	v_add_u32_e32 v137, 0xffffff4d, v136
	s_nop 0
	v_cndmask_b32_e32 v92, v234, v92, vcc
	v_cmp_lt_u32_e32 vcc, s69, v137
	v_add_u32_e32 v137, 0xffffff6c, v136
	s_nop 0
	v_cndmask_b32_e32 v76, v234, v76, vcc
	v_cmp_lt_u32_e32 vcc, s69, v137
	v_add_u32_e32 v137, 0xffffff4c, v136
	s_nop 0
	v_cndmask_b32_e32 v93, v234, v93, vcc
	v_cmp_lt_u32_e32 vcc, s69, v137
	v_add_u32_e32 v137, 0xffffff67, v136
	s_nop 0
	v_cndmask_b32_e32 v77, v234, v77, vcc
	v_cmp_lt_u32_e32 vcc, s69, v137
	v_add_u32_e32 v137, 0xffffff47, v136
	s_nop 0
	v_cndmask_b32_e32 v94, v234, v94, vcc
	v_cmp_lt_u32_e32 vcc, s69, v137
	v_add_u32_e32 v137, 0xffffff66, v136
	s_nop 0
	v_cndmask_b32_e32 v78, v234, v78, vcc
	v_cmp_lt_u32_e32 vcc, s69, v137
	v_add_u32_e32 v137, 0xffffff46, v136
	s_nop 0
	v_cndmask_b32_e32 v95, v234, v95, vcc
	v_cmp_lt_u32_e32 vcc, s69, v137
	v_add_u32_e32 v137, 0xffffff65, v136
	s_nop 0
	v_cndmask_b32_e32 v79, v234, v79, vcc
	v_cmp_lt_u32_e32 vcc, s69, v137
	v_add_u32_e32 v137, 0xffffff45, v136
	s_nop 0
	v_cndmask_b32_e32 v96, v234, v96, vcc
	v_cmp_lt_u32_e32 vcc, s69, v137
	v_add_u32_e32 v137, 0xffffff64, v136
	v_add_u32_e32 v136, 0xffffff44, v136
	v_cndmask_b32_e32 v80, v234, v80, vcc
	v_cmp_lt_u32_e32 vcc, s69, v137
	s_nop 1
	v_cndmask_b32_e32 v97, v234, v97, vcc
	v_cmp_lt_u32_e32 vcc, s69, v136
	s_nop 1
	v_cndmask_b32_e32 v81, v234, v81, vcc

.LBB0_402:
	s_add_u32 s0, s44, s48
	s_addc_u32 s1, s67, s49
	s_add_u32 s6, s0, 0x1800
	v_mul_lo_u32 v68, v133, s40
	s_addc_u32 s7, s1, 0
	v_or_b32_e32 v66, v68, v146
	v_mov_b32_e32 v67, v195
	s_mov_b32 m0, s63
	s_waitcnt vmcnt(2)
	s_barrier
	v_lshl_add_u64 v[66:67], v[66:67], 1, s[6:7]
	s_max_i32 s0, s29, 64
	global_load_lds_dwordx4 v[66:67], off
	v_add_u32_e32 v66, v68, v146
	v_mov_b32_e32 v67, v195
	s_sub_i32 s0, s0, 64
	v_lshl_add_u64 v[66:67], v[66:67], 1, s[6:7]
	s_mul_hi_u32 s7, s0, s40
	s_mul_i32 s6, s0, s40
	s_lshl_b64 s[6:7], s[6:7], 1
	s_add_u32 s6, s44, s6
	v_lshl_add_u64 v[66:67], v[66:67], 0, s[82:83]
	s_mov_b32 m0, s65
	s_addc_u32 s7, s67, s7
	global_load_lds_dwordx4 v[66:67], off
	v_lshl_add_u64 v[66:67], v[194:195], 1, s[6:7]
	v_lshl_add_u64 v[66:67], v[66:67], 0, s[86:87]
	s_mov_b32 m0, s57
	v_mul_lo_u32 v68, s40, v142
	global_load_lds_dwordx4 v[66:67], off
	v_lshl_add_u64 v[66:67], v[134:135], 1, s[6:7]
	s_mul_hi_u32 s7, s40, s29
	s_mul_i32 s6, s40, s29
	s_lshl_b64 s[6:7], s[6:7], 1
	s_add_u32 s0, s44, s6
	s_addc_u32 s1, s67, s7
	s_ashr_i32 s6, s54, 31
	s_mul_hi_u32 s7, s54, s40
	s_mul_i32 s6, s6, s40
	s_add_i32 s7, s7, s6
	s_mul_i32 s6, s54, s40
	s_lshl_b64 s[6:7], s[6:7], 1
	s_add_u32 s6, s0, s6
	s_addc_u32 s7, s1, s7
	s_lshl_b32 s0, s40, 2
	v_lshl_add_u64 v[66:67], v[66:67], 0, s[86:87]
	s_mov_b32 m0, s76
	v_or_b32_e32 v194, v68, v148
	v_add_u32_e32 v68, s0, v68
	global_load_lds_dwordx4 v[66:67], off
	v_lshl_add_u64 v[66:67], v[194:195], 1, s[6:7]
	s_mov_b32 m0, s62
	v_or_b32_e32 v194, v68, v150
	v_add_u32_e32 v68, s0, v68
	global_load_lds_dwordx4 v[66:67], off
	v_lshl_add_u64 v[66:67], v[194:195], 1, s[6:7]
	s_add_i32 m0, s62, 0x400
	v_or_b32_e32 v194, v68, v151
	v_add_u32_e32 v68, s0, v68
	global_load_lds_dwordx4 v[66:67], off
	v_lshl_add_u64 v[66:67], v[194:195], 1, s[6:7]
	s_add_i32 m0, s62, 0x800
	v_or_b32_e32 v194, v68, v152
	v_add_u32_e32 v68, s0, v68
	global_load_lds_dwordx4 v[66:67], off
	v_lshl_add_u64 v[66:67], v[194:195], 1, s[6:7]
	s_add_i32 m0, s62, 0xc00
	v_or_b32_e32 v194, v68, v148
	v_add_u32_e32 v68, s0, v68
	global_load_lds_dwordx4 v[66:67], off
	v_lshl_add_u64 v[66:67], v[194:195], 1, s[6:7]
	s_add_i32 m0, s62, 0x1000
	v_or_b32_e32 v194, v68, v150
	v_add_u32_e32 v68, s0, v68
	global_load_lds_dwordx4 v[66:67], off
	v_lshl_add_u64 v[66:67], v[194:195], 1, s[6:7]
	s_add_i32 m0, s62, 0x1400
	v_or_b32_e32 v194, v68, v151
	global_load_lds_dwordx4 v[66:67], off
	v_lshl_add_u64 v[66:67], v[194:195], 1, s[6:7]
	s_add_i32 m0, s62, 0x1800
	s_nop 0
	global_load_lds_dwordx4 v[66:67], off
	v_add_u32_e32 v66, s0, v68
	v_or_b32_e32 v194, v66, v152
	v_lshl_add_u64 v[66:67], v[194:195], 1, s[6:7]
	s_add_i32 m0, s62, 0x1c00
	s_cmp_lt_i32 s37, 6
	global_load_lds_dwordx4 v[66:67], off
	s_cselect_b64 s[6:7], -1, 0
	s_or_b32 s0, s11, 0xff
	s_cmp_lt_i32 s0, s64
	s_cselect_b64 s[40:41], -1, 0
	s_or_b64 s[6:7], s[6:7], s[40:41]
	s_and_b64 vcc, exec, s[6:7]
	s_cbranch_vccnz .LBB0_408
	s_cmp_gt_u32 s37, 7
	s_cselect_b64 s[6:7], -1, 0
	s_addk_i32 s22, 0xff9e
	s_cmp_gt_i32 s43, s22
	s_cselect_b64 s[40:41], -1, 0
	s_and_b64 s[6:7], s[6:7], s[40:41]
	s_and_b64 vcc, exec, s[6:7]
	ds_read_b128 v[204:207], v167
	ds_read_b128 v[208:211], v168
	ds_read_b128 v[212:215], v169
	ds_read_b128 v[216:219], v170
	ds_read_b128 v[220:223], v167 offset:128
	ds_read_b128 v[224:227], v168 offset:128
	ds_read_b128 v[228:231], v169 offset:128
	ds_read_b128 v[240:243], v170 offset:128
	ds_read_b128 v[244:247], v167 offset:8192
	ds_read_b128 v[248:251], v168 offset:8192
	ds_read_b128 v[190:193], v169 offset:8192
	s_waitcnt lgkmcnt(10)
	v_mfma_f32_32x32x16_bf16 v[82:97], v[204:207], v[126:129], 0
	s_waitcnt lgkmcnt(9)
	v_mfma_f32_32x32x16_bf16 v[82:97], v[208:211], v[118:121], v[82:97]
	s_waitcnt lgkmcnt(8)
	v_mfma_f32_32x32x16_bf16 v[82:97], v[212:215], v[122:125], v[82:97]
	s_waitcnt lgkmcnt(7)
	v_mfma_f32_32x32x16_bf16 v[82:97], v[216:219], v[114:117], v[82:97]
	s_waitcnt lgkmcnt(6)
	v_mfma_f32_32x32x16_bf16 v[82:97], v[220:223], v[110:113], v[82:97]
	ds_read_b128 v[204:207], v170 offset:8192
	ds_read_b128 v[208:211], v167 offset:8320
	ds_read_b128 v[212:215], v168 offset:8320
	ds_read_b128 v[216:219], v169 offset:8320
	ds_read_b128 v[220:223], v170 offset:8320
	s_waitcnt lgkmcnt(10)
	v_mfma_f32_32x32x16_bf16 v[82:97], v[224:227], v[106:109], v[82:97]
	s_waitcnt lgkmcnt(9)
	v_mfma_f32_32x32x16_bf16 v[82:97], v[228:231], v[102:105], v[82:97]
	s_waitcnt lgkmcnt(8)
	v_mfma_f32_32x32x16_bf16 v[82:97], v[240:243], v[98:101], v[82:97]
	s_waitcnt lgkmcnt(7)
	v_mfma_f32_32x32x16_bf16 v[66:81], v[244:247], v[126:129], 0
	s_waitcnt lgkmcnt(6)
	v_mfma_f32_32x32x16_bf16 v[66:81], v[248:251], v[118:121], v[66:81]
	s_waitcnt lgkmcnt(5)
	v_mfma_f32_32x32x16_bf16 v[66:81], v[190:193], v[122:125], v[66:81]
	s_waitcnt lgkmcnt(4)
	v_mfma_f32_32x32x16_bf16 v[66:81], v[204:207], v[114:117], v[66:81]
	s_waitcnt lgkmcnt(3)
	v_mfma_f32_32x32x16_bf16 v[66:81], v[208:211], v[110:113], v[66:81]
	s_waitcnt lgkmcnt(2)
	v_mfma_f32_32x32x16_bf16 v[66:81], v[212:215], v[106:109], v[66:81]
	s_waitcnt lgkmcnt(1)
	v_mfma_f32_32x32x16_bf16 v[66:81], v[216:219], v[102:105], v[66:81]
	s_waitcnt lgkmcnt(0)
	v_mfma_f32_32x32x16_bf16 v[66:81], v[220:223], v[98:101], v[66:81]
	s_cbranch_vccnz .LBB0_405
	v_subrev_u32_e32 v1, s43, v1
	s_movk_i32 s0, 0x81
	v_cmp_gt_u32_e32 vcc, s0, v1
	v_add_u32_e32 v98, 0xffffff5f, v1
	s_nop 5
	v_cndmask_b32_e32 v82, v234, v82, vcc
	v_cmp_lt_u32_e32 vcc, s69, v98
	v_add_u32_e32 v98, 0xffffff7e, v1
	s_nop 0
	v_cndmask_b32_e32 v66, v234, v66, vcc
	v_cmp_lt_u32_e32 vcc, s69, v98
	v_add_u32_e32 v98, 0xffffff5e, v1
	s_nop 0
	v_cndmask_b32_e32 v83, v234, v83, vcc
	v_cmp_lt_u32_e32 vcc, s69, v98
	v_add_u32_e32 v98, 0xffffff7d, v1
	s_nop 0
	v_cndmask_b32_e32 v67, v234, v67, vcc
	v_cmp_lt_u32_e32 vcc, s69, v98
	v_add_u32_e32 v98, 0xffffff5d, v1
	s_nop 0
	v_cndmask_b32_e32 v84, v234, v84, vcc
	v_cmp_lt_u32_e32 vcc, s69, v98
	v_add_u32_e32 v98, 0xffffff7c, v1
	s_nop 0
	v_cndmask_b32_e32 v68, v234, v68, vcc
	v_cmp_lt_u32_e32 vcc, s69, v98
	v_add_u32_e32 v98, 0xffffff5c, v1
	s_nop 0
	v_cndmask_b32_e32 v85, v234, v85, vcc
	v_cmp_lt_u32_e32 vcc, s69, v98
	v_add_u32_e32 v98, 0xffffff77, v1
	s_nop 0
	v_cndmask_b32_e32 v69, v234, v69, vcc
	v_cmp_lt_u32_e32 vcc, s69, v98
	v_add_u32_e32 v98, 0xffffff57, v1
	s_nop 0
	v_cndmask_b32_e32 v86, v234, v86, vcc
	v_cmp_lt_u32_e32 vcc, s69, v98
	v_add_u32_e32 v98, 0xffffff76, v1
	s_nop 0
	v_cndmask_b32_e32 v70, v234, v70, vcc
	v_cmp_lt_u32_e32 vcc, s69, v98
	v_add_u32_e32 v98, 0xffffff56, v1
	s_nop 0
	v_cndmask_b32_e32 v87, v234, v87, vcc
	v_cmp_lt_u32_e32 vcc, s69, v98
	v_add_u32_e32 v98, 0xffffff75, v1
	s_nop 0
	v_cndmask_b32_e32 v71, v234, v71, vcc
	v_cmp_lt_u32_e32 vcc, s69, v98
	v_add_u32_e32 v98, 0xffffff55, v1
	s_nop 0
	v_cndmask_b32_e32 v88, v234, v88, vcc
	v_cmp_lt_u32_e32 vcc, s69, v98
	v_add_u32_e32 v98, 0xffffff74, v1
	s_nop 0
	v_cndmask_b32_e32 v72, v234, v72, vcc
	v_cmp_lt_u32_e32 vcc, s69, v98
	v_add_u32_e32 v98, 0xffffff54, v1
	s_nop 0
	v_cndmask_b32_e32 v89, v234, v89, vcc
	v_cmp_lt_u32_e32 vcc, s69, v98
	v_add_u32_e32 v98, 0xffffff6f, v1
	s_nop 0
	v_cndmask_b32_e32 v73, v234, v73, vcc
	v_cmp_lt_u32_e32 vcc, s69, v98
	v_add_u32_e32 v98, 0xffffff4f, v1
	s_nop 0
	v_cndmask_b32_e32 v90, v234, v90, vcc
	v_cmp_lt_u32_e32 vcc, s69, v98
	v_add_u32_e32 v98, 0xffffff6e, v1
	s_nop 0
	v_cndmask_b32_e32 v74, v234, v74, vcc
	v_cmp_lt_u32_e32 vcc, s69, v98
	v_add_u32_e32 v98, 0xffffff4e, v1
	s_nop 0
	v_cndmask_b32_e32 v91, v234, v91, vcc
	v_cmp_lt_u32_e32 vcc, s69, v98
	v_add_u32_e32 v98, 0xffffff6d, v1
	s_nop 0
	v_cndmask_b32_e32 v75, v234, v75, vcc
	v_cmp_lt_u32_e32 vcc, s69, v98
	v_add_u32_e32 v98, 0xffffff4d, v1
	s_nop 0
	v_cndmask_b32_e32 v92, v234, v92, vcc
	v_cmp_lt_u32_e32 vcc, s69, v98
	v_add_u32_e32 v98, 0xffffff6c, v1
	s_nop 0
	v_cndmask_b32_e32 v76, v234, v76, vcc
	v_cmp_lt_u32_e32 vcc, s69, v98
	v_add_u32_e32 v98, 0xffffff4c, v1
	s_nop 0
	v_cndmask_b32_e32 v93, v234, v93, vcc
	v_cmp_lt_u32_e32 vcc, s69, v98
	v_add_u32_e32 v98, 0xffffff67, v1
	s_nop 0
	v_cndmask_b32_e32 v77, v234, v77, vcc
	v_cmp_lt_u32_e32 vcc, s69, v98
	v_add_u32_e32 v98, 0xffffff47, v1
	s_nop 0
	v_cndmask_b32_e32 v94, v234, v94, vcc
	v_cmp_lt_u32_e32 vcc, s69, v98
	v_add_u32_e32 v98, 0xffffff66, v1
	s_nop 0
	v_cndmask_b32_e32 v78, v234, v78, vcc
	v_cmp_lt_u32_e32 vcc, s69, v98
	v_add_u32_e32 v98, 0xffffff46, v1
	s_nop 0
	v_cndmask_b32_e32 v95, v234, v95, vcc
	v_cmp_lt_u32_e32 vcc, s69, v98
	v_add_u32_e32 v98, 0xffffff65, v1
	s_nop 0
	v_cndmask_b32_e32 v79, v234, v79, vcc
	v_cmp_lt_u32_e32 vcc, s69, v98
	v_add_u32_e32 v98, 0xffffff45, v1
	s_nop 0
	v_cndmask_b32_e32 v96, v234, v96, vcc
	v_cmp_lt_u32_e32 vcc, s69, v98
	v_add_u32_e32 v98, 0xffffff64, v1
	v_add_u32_e32 v1, 0xffffff44, v1
	v_cndmask_b32_e32 v80, v234, v80, vcc
	v_cmp_lt_u32_e32 vcc, s69, v98
	s_nop 1
	v_cndmask_b32_e32 v97, v234, v97, vcc
	v_cmp_lt_u32_e32 vcc, s69, v1
	s_nop 1
	v_cndmask_b32_e32 v81, v234, v81, vcc
